# v64 + M1 epilogue act stores with the nt (streaming) cache hint
# baseline (speedup 1.0000x reference)
.LBB0_1375:
	s_add_i32 s9, s8, 0x10000
	s_and_b32 s10, s9, 0x10000
	v_add_u32_e32 v246, s10, v128
	s_and_b32 s8, s8, 0x10000
	v_add_u32_e32 v153, s8, v152
	v_add_u32_e32 v154, s8, v151
	s_waitcnt vmcnt(0) lgkmcnt(0)
	s_barrier
	v_add_u32_e32 v181, v153, v149
	ds_read_b128 v[182:185], v181 offset:0x0
	ds_read_b128 v[186:189], v181 offset:0x1000
	ds_read_b128 v[190:193], v181 offset:0x2000
	ds_read_b128 v[194:197], v181 offset:0x3000
	v_add_u32_e32 v181, v154, v149
	ds_read_b128 v[198:201], v181 offset:0x0
	ds_read_b128 v[202:205], v181 offset:0x1000
	v_mfma_f32_32x32x16_bf16 v[112:127], v[206:209], v[222:225], v[112:127]
	v_mfma_f32_32x32x16_bf16 v[48:63], v[206:209], v[226:229], v[48:63]
	v_lshl_add_u64 v[244:245], v[134:135], 0, s[4:5]
	v_lshl_add_u64 v[244:245], v[244:245], 0, s[90:91]
	v_readfirstlane_b32 s10, v246
	s_mov_b32 m0, s10
	s_nop 0
	global_load_lds_dwordx4 v[244:245], off
	v_mfma_f32_32x32x16_bf16 v[96:111], v[210:213], v[222:225], v[96:111]
	v_mfma_f32_32x32x16_bf16 v[32:47], v[210:213], v[226:229], v[32:47]
	v_add_u32_e32 v243, 0x2000, v246
	v_lshl_add_u64 v[244:245], v[134:135], 0, s[4:5]
	v_lshl_add_u64 v[244:245], v[244:245], 0, s[16:17]
	v_readfirstlane_b32 s10, v243
	s_mov_b32 m0, s10
	s_nop 0
	global_load_lds_dwordx4 v[244:245], off
	v_mfma_f32_32x32x16_bf16 v[80:95], v[214:217], v[222:225], v[80:95]
	v_mfma_f32_32x32x16_bf16 v[16:31], v[214:217], v[226:229], v[16:31]
	v_add_u32_e32 v243, 0x4000, v246
	v_lshl_add_u64 v[244:245], v[134:135], 0, s[4:5]
	v_lshl_add_u64 v[244:245], v[244:245], 0, s[20:21]
	v_readfirstlane_b32 s10, v243
	s_mov_b32 m0, s10
	s_nop 0
	global_load_lds_dwordx4 v[244:245], off
	v_mfma_f32_32x32x16_bf16 v[64:79], v[218:221], v[222:225], v[64:79]
	v_mfma_f32_32x32x16_bf16 v[0:15], v[218:221], v[226:229], v[0:15]
	v_add_u32_e32 v243, 0x6000, v246
	v_lshl_add_u64 v[244:245], v[134:135], 0, s[4:5]
	v_lshl_add_u64 v[244:245], v[244:245], 0, s[12:13]
	v_readfirstlane_b32 s10, v243
	s_mov_b32 m0, s10
	s_nop 0
	global_load_lds_dwordx4 v[244:245], off
	v_add_u32_e32 v181, v153, v148
	ds_read_b128 v[206:209], v181 offset:0x0
	ds_read_b128 v[210:213], v181 offset:0x1000
	ds_read_b128 v[214:217], v181 offset:0x2000
	ds_read_b128 v[218:221], v181 offset:0x3000
	v_add_u32_e32 v181, v154, v148
	ds_read_b128 v[222:225], v181 offset:0x0
	ds_read_b128 v[226:229], v181 offset:0x1000
	s_waitcnt lgkmcnt(6)
	v_mfma_f32_32x32x16_bf16 v[112:127], v[182:185], v[198:201], v[112:127]
	v_mfma_f32_32x32x16_bf16 v[48:63], v[182:185], v[202:205], v[48:63]
	v_add_u32_e32 v243, 0x8000, v246
	s_mov_b64 s[10:11], 0x1314080
	v_lshl_add_u64 v[244:245], v[132:133], 0, s[4:5]
	v_lshl_add_u64 v[244:245], v[244:245], 0, s[10:11]
	v_readfirstlane_b32 s10, v243
	s_mov_b32 m0, s10
	s_nop 0
	global_load_lds_dwordx4 v[244:245], off
	v_mfma_f32_32x32x16_bf16 v[96:111], v[186:189], v[198:201], v[96:111]
	v_mfma_f32_32x32x16_bf16 v[32:47], v[186:189], v[202:205], v[32:47]
	v_add_u32_e32 v243, 0xa000, v246
	s_mov_b64 s[10:11], 0x1334080
	v_lshl_add_u64 v[244:245], v[132:133], 0, s[4:5]
	v_lshl_add_u64 v[244:245], v[244:245], 0, s[10:11]
	v_readfirstlane_b32 s10, v243
	s_mov_b32 m0, s10
	s_nop 0
	global_load_lds_dwordx4 v[244:245], off
	v_mfma_f32_32x32x16_bf16 v[80:95], v[190:193], v[198:201], v[80:95]
	v_mfma_f32_32x32x16_bf16 v[16:31], v[190:193], v[202:205], v[16:31]
	v_add_u32_e32 v243, 0xc000, v246
	s_mov_b64 s[10:11], 0x1354080
	v_lshl_add_u64 v[244:245], v[132:133], 0, s[4:5]
	v_lshl_add_u64 v[244:245], v[244:245], 0, s[10:11]
	v_readfirstlane_b32 s10, v243
	s_mov_b32 m0, s10
	s_nop 0
	global_load_lds_dwordx4 v[244:245], off
	v_mfma_f32_32x32x16_bf16 v[64:79], v[194:197], v[198:201], v[64:79]
	v_mfma_f32_32x32x16_bf16 v[0:15], v[194:197], v[202:205], v[0:15]
	v_add_u32_e32 v243, 0xe000, v246
	s_mov_b64 s[10:11], 0x1374080
	v_lshl_add_u64 v[244:245], v[132:133], 0, s[4:5]
	v_lshl_add_u64 v[244:245], v[244:245], 0, s[10:11]
	v_readfirstlane_b32 s10, v243
	s_mov_b32 m0, s10
	s_nop 0
	global_load_lds_dwordx4 v[244:245], off
	v_add_u32_e32 v181, v153, v147
	ds_read_b128 v[182:185], v181 offset:0x0
	ds_read_b128 v[186:189], v181 offset:0x1000
	ds_read_b128 v[190:193], v181 offset:0x2000
	ds_read_b128 v[194:197], v181 offset:0x3000
	v_add_u32_e32 v181, v154, v147
	ds_read_b128 v[198:201], v181 offset:0x0
	ds_read_b128 v[202:205], v181 offset:0x1000
	s_waitcnt lgkmcnt(6)
	v_mfma_f32_32x32x16_bf16 v[112:127], v[206:209], v[222:225], v[112:127]
	v_mfma_f32_32x32x16_bf16 v[48:63], v[206:209], v[226:229], v[48:63]
	v_mfma_f32_32x32x16_bf16 v[96:111], v[210:213], v[222:225], v[96:111]
	v_mfma_f32_32x32x16_bf16 v[32:47], v[210:213], v[226:229], v[32:47]
	v_mfma_f32_32x32x16_bf16 v[80:95], v[214:217], v[222:225], v[80:95]
	v_mfma_f32_32x32x16_bf16 v[16:31], v[214:217], v[226:229], v[16:31]
	v_mfma_f32_32x32x16_bf16 v[64:79], v[218:221], v[222:225], v[64:79]
	v_mfma_f32_32x32x16_bf16 v[0:15], v[218:221], v[226:229], v[0:15]
	v_add_u32_e32 v181, v153, v146
	ds_read_b128 v[206:209], v181 offset:0x0
	ds_read_b128 v[210:213], v181 offset:0x1000
	ds_read_b128 v[214:217], v181 offset:0x2000
	ds_read_b128 v[218:221], v181 offset:0x3000
	v_add_u32_e32 v181, v154, v146
	ds_read_b128 v[222:225], v181 offset:0x0
	ds_read_b128 v[226:229], v181 offset:0x1000
	s_waitcnt lgkmcnt(6)
	v_mfma_f32_32x32x16_bf16 v[112:127], v[182:185], v[198:201], v[112:127]
	v_mfma_f32_32x32x16_bf16 v[48:63], v[182:185], v[202:205], v[48:63]
	v_mfma_f32_32x32x16_bf16 v[96:111], v[186:189], v[198:201], v[96:111]
	v_mfma_f32_32x32x16_bf16 v[32:47], v[186:189], v[202:205], v[32:47]
	v_mfma_f32_32x32x16_bf16 v[80:95], v[190:193], v[198:201], v[80:95]
	v_mfma_f32_32x32x16_bf16 v[16:31], v[190:193], v[202:205], v[16:31]
	v_mfma_f32_32x32x16_bf16 v[64:79], v[194:197], v[198:201], v[64:79]
	v_mfma_f32_32x32x16_bf16 v[0:15], v[194:197], v[202:205], v[0:15]
	s_waitcnt lgkmcnt(0)
	s_add_u32 s4, s4, 0x80
	s_addc_u32 s5, s5, 0
	s_mov_b32 s8, s9
	s_cmpk_lg_i32 s4, 0x780
	s_cbranch_scc1 .LBB0_1375
	s_and_b32 s8, s8, 0x10000
	v_add_u32_e32 v153, s8, v152
	v_add_u32_e32 v154, s8, v151
	s_waitcnt vmcnt(0) lgkmcnt(0)
	s_barrier
	v_add_u32_e32 v181, v153, v149
	ds_read_b128 v[182:185], v181 offset:0x0
	ds_read_b128 v[186:189], v181 offset:0x1000
	ds_read_b128 v[190:193], v181 offset:0x2000
	ds_read_b128 v[194:197], v181 offset:0x3000
	v_add_u32_e32 v181, v154, v149
	ds_read_b128 v[198:201], v181 offset:0x0
	ds_read_b128 v[202:205], v181 offset:0x1000
	v_mfma_f32_32x32x16_bf16 v[112:127], v[206:209], v[222:225], v[112:127]
	v_mfma_f32_32x32x16_bf16 v[48:63], v[206:209], v[226:229], v[48:63]
	v_mfma_f32_32x32x16_bf16 v[96:111], v[210:213], v[222:225], v[96:111]
	v_mfma_f32_32x32x16_bf16 v[32:47], v[210:213], v[226:229], v[32:47]
	v_mfma_f32_32x32x16_bf16 v[80:95], v[214:217], v[222:225], v[80:95]
	v_mfma_f32_32x32x16_bf16 v[16:31], v[214:217], v[226:229], v[16:31]
	v_mfma_f32_32x32x16_bf16 v[64:79], v[218:221], v[222:225], v[64:79]
	v_mfma_f32_32x32x16_bf16 v[0:15], v[218:221], v[226:229], v[0:15]
	v_add_u32_e32 v181, v153, v148
	ds_read_b128 v[206:209], v181 offset:0x0
	ds_read_b128 v[210:213], v181 offset:0x1000
	ds_read_b128 v[214:217], v181 offset:0x2000
	ds_read_b128 v[218:221], v181 offset:0x3000
	v_add_u32_e32 v181, v154, v148
	ds_read_b128 v[222:225], v181 offset:0x0
	ds_read_b128 v[226:229], v181 offset:0x1000
	s_waitcnt lgkmcnt(6)
	v_mfma_f32_32x32x16_bf16 v[112:127], v[182:185], v[198:201], v[112:127]
	v_mfma_f32_32x32x16_bf16 v[48:63], v[182:185], v[202:205], v[48:63]
	v_mfma_f32_32x32x16_bf16 v[96:111], v[186:189], v[198:201], v[96:111]
	v_mfma_f32_32x32x16_bf16 v[32:47], v[186:189], v[202:205], v[32:47]
	v_mfma_f32_32x32x16_bf16 v[80:95], v[190:193], v[198:201], v[80:95]
	v_mfma_f32_32x32x16_bf16 v[16:31], v[190:193], v[202:205], v[16:31]
	v_mfma_f32_32x32x16_bf16 v[64:79], v[194:197], v[198:201], v[64:79]
	v_mfma_f32_32x32x16_bf16 v[0:15], v[194:197], v[202:205], v[0:15]
	v_add_u32_e32 v181, v153, v147
	ds_read_b128 v[182:185], v181 offset:0x0
	ds_read_b128 v[186:189], v181 offset:0x1000
	ds_read_b128 v[190:193], v181 offset:0x2000
	ds_read_b128 v[194:197], v181 offset:0x3000
	v_add_u32_e32 v181, v154, v147
	ds_read_b128 v[198:201], v181 offset:0x0
	ds_read_b128 v[202:205], v181 offset:0x1000
	s_waitcnt lgkmcnt(6)
	v_mfma_f32_32x32x16_bf16 v[112:127], v[206:209], v[222:225], v[112:127]
	v_mfma_f32_32x32x16_bf16 v[48:63], v[206:209], v[226:229], v[48:63]
	v_mfma_f32_32x32x16_bf16 v[96:111], v[210:213], v[222:225], v[96:111]
	v_mfma_f32_32x32x16_bf16 v[32:47], v[210:213], v[226:229], v[32:47]
	v_mfma_f32_32x32x16_bf16 v[80:95], v[214:217], v[222:225], v[80:95]
	v_mfma_f32_32x32x16_bf16 v[16:31], v[214:217], v[226:229], v[16:31]
	v_mfma_f32_32x32x16_bf16 v[64:79], v[218:221], v[222:225], v[64:79]
	v_mfma_f32_32x32x16_bf16 v[0:15], v[218:221], v[226:229], v[0:15]
	v_add_u32_e32 v181, v153, v146
	ds_read_b128 v[206:209], v181 offset:0x0
	ds_read_b128 v[210:213], v181 offset:0x1000
	ds_read_b128 v[214:217], v181 offset:0x2000
	ds_read_b128 v[218:221], v181 offset:0x3000
	v_add_u32_e32 v181, v154, v146
	ds_read_b128 v[222:225], v181 offset:0x0
	ds_read_b128 v[226:229], v181 offset:0x1000
	s_waitcnt lgkmcnt(6)
	v_mfma_f32_32x32x16_bf16 v[112:127], v[182:185], v[198:201], v[112:127]
	v_mfma_f32_32x32x16_bf16 v[48:63], v[182:185], v[202:205], v[48:63]
	v_mfma_f32_32x32x16_bf16 v[96:111], v[186:189], v[198:201], v[96:111]
	v_mfma_f32_32x32x16_bf16 v[32:47], v[186:189], v[202:205], v[32:47]
	v_mfma_f32_32x32x16_bf16 v[80:95], v[190:193], v[198:201], v[80:95]
	v_mfma_f32_32x32x16_bf16 v[16:31], v[190:193], v[202:205], v[16:31]
	v_mfma_f32_32x32x16_bf16 v[64:79], v[194:197], v[198:201], v[64:79]
	v_mfma_f32_32x32x16_bf16 v[0:15], v[194:197], v[202:205], v[0:15]
	s_waitcnt lgkmcnt(0)
	v_mfma_f32_32x32x16_bf16 v[112:127], v[206:209], v[222:225], v[112:127]
	v_mfma_f32_32x32x16_bf16 v[48:63], v[206:209], v[226:229], v[48:63]
	v_mfma_f32_32x32x16_bf16 v[96:111], v[210:213], v[222:225], v[96:111]
	v_mfma_f32_32x32x16_bf16 v[32:47], v[210:213], v[226:229], v[32:47]
	v_mfma_f32_32x32x16_bf16 v[80:95], v[214:217], v[222:225], v[80:95]
	v_mfma_f32_32x32x16_bf16 v[16:31], v[214:217], v[226:229], v[16:31]
	v_mfma_f32_32x32x16_bf16 v[64:79], v[218:221], v[222:225], v[64:79]
	v_mfma_f32_32x32x16_bf16 v[0:15], v[218:221], v[226:229], v[0:15]
	v_lshrrev_b32_e32 v130, 3, v130
	v_lshlrev_b32_e32 v132, 2, v137
	v_lshlrev_b32_e32 v133, 2, v144
	s_mov_b32 s4, 0x24000
	v_and_b32_e32 v147, 4, v130
	v_add3_u32 v146, v132, v133, s4
	v_lshlrev_b32_e32 v130, 2, v136
	v_lshlrev_b32_e32 v132, 2, v147
	s_mov_b32 s4, 0x24400
	s_barrier
	v_add3_u32 v130, v130, v132, s4
	ds_read_b32 v148, v146
	ds_read_b128 v[132:135], v130
	s_movk_i32 s4, 0x2400
	v_mul_lo_u32 v145, v145, s4
	s_movk_i32 s4, 0x110
	v_mad_u32_u24 v144, v144, s4, v145
	s_waitcnt lgkmcnt(0)
	v_fma_f32 v112, v112, v148, v132
	v_fma_f32 v113, v113, v148, v133
	v_max_f32_e32 v112, 0, v112
	v_max_f32_e32 v113, 0, v113
	v_fma_f32 v114, v114, v148, v134
	v_fmac_f32_e32 v135, v115, v148
	v_max_f32_e32 v132, 0, v114
	v_max_f32_e32 v115, 0, v135
	v_mul_f32_e32 v112, v112, v112
	v_mul_f32_e32 v113, v113, v113
	v_cvt_pk_bf16_f32 v114, v112, v113
	v_mul_f32_e32 v112, v132, v132
	v_mul_f32_e32 v113, v115, v115
	v_cvt_pk_bf16_f32 v115, v112, v113
	v_lshl_or_b32 v112, v147, 1, v144
	ds_write_b64 v112, v[114:115]
	ds_read_b128 v[132:135], v130 offset:32
	v_and_b32_e32 v128, 0xf0, v128
	s_add_i32 s7, s7, s38
	s_cmpk_gt_i32 s7, 0x2ff
	s_waitcnt lgkmcnt(0)
	v_fma_f32 v113, v116, v148, v132
	v_fma_f32 v114, v117, v148, v133
	v_max_f32_e32 v113, 0, v113
	v_max_f32_e32 v114, 0, v114
	v_fma_f32 v115, v118, v148, v134
	v_fmac_f32_e32 v135, v119, v148
	v_max_f32_e32 v115, 0, v115
	v_max_f32_e32 v116, 0, v135
	v_mul_f32_e32 v113, v113, v113
	v_mul_f32_e32 v114, v114, v114
	v_cvt_pk_bf16_f32 v114, v113, v114
	v_mul_f32_e32 v113, v115, v115
	v_mul_f32_e32 v115, v116, v116
	v_cvt_pk_bf16_f32 v115, v113, v115
	ds_write_b64 v112, v[114:115] offset:16
	ds_read_b128 v[114:117], v130 offset:64
	s_waitcnt lgkmcnt(0)
	v_fma_f32 v113, v120, v148, v114
	v_fma_f32 v114, v121, v148, v115
	v_max_f32_e32 v113, 0, v113
	v_max_f32_e32 v114, 0, v114
	v_fma_f32 v115, v122, v148, v116
	v_fmac_f32_e32 v117, v123, v148
	v_max_f32_e32 v115, 0, v115
	v_max_f32_e32 v116, 0, v117
	v_mul_f32_e32 v113, v113, v113
	v_mul_f32_e32 v114, v114, v114
	v_cvt_pk_bf16_f32 v114, v113, v114
	v_mul_f32_e32 v113, v115, v115
	v_mul_f32_e32 v115, v116, v116
	v_cvt_pk_bf16_f32 v115, v113, v115
	ds_write_b64 v112, v[114:115] offset:32
	ds_read_b128 v[114:117], v130 offset:96
	s_waitcnt lgkmcnt(0)
	v_fma_f32 v113, v124, v148, v114
	v_fma_f32 v114, v125, v148, v115
	v_max_f32_e32 v113, 0, v113
	v_max_f32_e32 v114, 0, v114
	v_fma_f32 v115, v126, v148, v116
	v_fmac_f32_e32 v117, v127, v148
	v_max_f32_e32 v115, 0, v115
	v_max_f32_e32 v116, 0, v117
	v_mul_f32_e32 v113, v113, v113
	v_mul_f32_e32 v114, v114, v114
	v_cvt_pk_bf16_f32 v114, v113, v114
	v_mul_f32_e32 v113, v115, v115
	v_mul_f32_e32 v115, v116, v116
	v_cvt_pk_bf16_f32 v115, v113, v115
	ds_write_b64 v112, v[114:115] offset:48
	ds_read_b128 v[114:117], v130 offset:128
	s_waitcnt lgkmcnt(0)
	v_fma_f32 v96, v96, v148, v114
	v_fma_f32 v97, v97, v148, v115
	v_max_f32_e32 v96, 0, v96
	v_max_f32_e32 v97, 0, v97
	v_fma_f32 v98, v98, v148, v116
	v_fmac_f32_e32 v117, v99, v148
	v_max_f32_e32 v98, 0, v98
	v_max_f32_e32 v99, 0, v117
	v_mul_f32_e32 v96, v96, v96
	v_mul_f32_e32 v97, v97, v97
	v_cvt_pk_bf16_f32 v96, v96, v97
	v_mul_f32_e32 v97, v98, v98
	v_mul_f32_e32 v98, v99, v99
	v_cvt_pk_bf16_f32 v97, v97, v98
	ds_write_b64 v112, v[96:97] offset:64
	ds_read_b128 v[96:99], v130 offset:160
	s_waitcnt lgkmcnt(0)
	v_fma_f32 v96, v100, v148, v96
	v_fma_f32 v97, v101, v148, v97
	v_max_f32_e32 v96, 0, v96
	v_max_f32_e32 v97, 0, v97
	v_fma_f32 v98, v102, v148, v98
	v_fmac_f32_e32 v99, v103, v148
	v_max_f32_e32 v98, 0, v98
	v_max_f32_e32 v99, 0, v99
	v_mul_f32_e32 v96, v96, v96
	v_mul_f32_e32 v97, v97, v97
	v_cvt_pk_bf16_f32 v96, v96, v97
	v_mul_f32_e32 v97, v98, v98
	v_mul_f32_e32 v98, v99, v99
	v_cvt_pk_bf16_f32 v97, v97, v98
	ds_write_b64 v112, v[96:97] offset:80
	ds_read_b128 v[96:99], v130 offset:192
	v_add_u32_e32 v102, s2, v136
	v_ashrrev_i32_e32 v103, 31, v102
	s_waitcnt lgkmcnt(0)
	v_fma_f32 v96, v104, v148, v96
	v_fma_f32 v97, v105, v148, v97
	v_max_f32_e32 v96, 0, v96
	v_max_f32_e32 v97, 0, v97
	v_fma_f32 v98, v106, v148, v98
	v_fmac_f32_e32 v99, v107, v148
	v_max_f32_e32 v98, 0, v98
	v_max_f32_e32 v99, 0, v99
	v_mul_f32_e32 v96, v96, v96
	v_mul_f32_e32 v97, v97, v97
	v_cvt_pk_bf16_f32 v96, v96, v97
	v_mul_f32_e32 v97, v98, v98
	v_mul_f32_e32 v98, v99, v99
	v_cvt_pk_bf16_f32 v97, v97, v98
	ds_write_b64 v112, v[96:97] offset:96
	ds_read_b128 v[96:99], v130 offset:224
	v_add_u32_e32 v106, s3, v137
	v_lshrrev_b32_e32 v107, 4, v131
	s_waitcnt lgkmcnt(0)
	v_fma_f32 v96, v108, v148, v96
	v_fma_f32 v97, v109, v148, v97
	v_max_f32_e32 v96, 0, v96
	v_max_f32_e32 v97, 0, v97
	v_fma_f32 v98, v110, v148, v98
	v_fmac_f32_e32 v99, v111, v148
	v_max_f32_e32 v98, 0, v98
	v_max_f32_e32 v99, 0, v99
	v_mul_f32_e32 v96, v96, v96
	v_mul_f32_e32 v97, v97, v97
	v_cvt_pk_bf16_f32 v96, v96, v97
	v_mul_f32_e32 v97, v98, v98
	v_mul_f32_e32 v98, v99, v99
	v_cvt_pk_bf16_f32 v97, v97, v98
	ds_write_b64 v112, v[96:97] offset:112
	ds_read_b128 v[96:99], v130 offset:256
	s_waitcnt lgkmcnt(0)
	v_fma_f32 v80, v80, v148, v96
	v_fma_f32 v81, v81, v148, v97
	v_max_f32_e32 v80, 0, v80
	v_max_f32_e32 v81, 0, v81
	v_fma_f32 v82, v82, v148, v98
	v_fmac_f32_e32 v99, v83, v148
	v_max_f32_e32 v82, 0, v82
	v_max_f32_e32 v83, 0, v99
	v_mul_f32_e32 v80, v80, v80
	v_mul_f32_e32 v81, v81, v81
	v_cvt_pk_bf16_f32 v80, v80, v81
	v_mul_f32_e32 v81, v82, v82
	v_mul_f32_e32 v82, v83, v83
	v_cvt_pk_bf16_f32 v81, v81, v82
	ds_write_b64 v112, v[80:81] offset:128
	ds_read_b128 v[80:83], v130 offset:288
	s_waitcnt lgkmcnt(0)
	v_fma_f32 v80, v84, v148, v80
	v_fma_f32 v81, v85, v148, v81
	v_max_f32_e32 v80, 0, v80
	v_max_f32_e32 v81, 0, v81
	v_fma_f32 v82, v86, v148, v82
	v_fmac_f32_e32 v83, v87, v148
	v_max_f32_e32 v82, 0, v82
	v_max_f32_e32 v83, 0, v83
	v_mul_f32_e32 v80, v80, v80
	v_mul_f32_e32 v81, v81, v81
	v_cvt_pk_bf16_f32 v80, v80, v81
	v_mul_f32_e32 v81, v82, v82
	v_mul_f32_e32 v82, v83, v83
	v_cvt_pk_bf16_f32 v81, v81, v82
	ds_write_b64 v112, v[80:81] offset:144
	ds_read_b128 v[80:83], v130 offset:320
	s_waitcnt lgkmcnt(0)
	v_fma_f32 v80, v88, v148, v80
	v_fma_f32 v81, v89, v148, v81
	v_max_f32_e32 v80, 0, v80
	v_max_f32_e32 v81, 0, v81
	v_fma_f32 v82, v90, v148, v82
	v_fmac_f32_e32 v83, v91, v148
	v_max_f32_e32 v82, 0, v82
	v_max_f32_e32 v83, 0, v83
	v_mul_f32_e32 v80, v80, v80
	v_mul_f32_e32 v81, v81, v81
	v_cvt_pk_bf16_f32 v80, v80, v81
	v_mul_f32_e32 v81, v82, v82
	v_mul_f32_e32 v82, v83, v83
	v_cvt_pk_bf16_f32 v81, v81, v82
	ds_write_b64 v112, v[80:81] offset:160
	ds_read_b128 v[80:83], v130 offset:352
	s_waitcnt lgkmcnt(0)
	v_fma_f32 v80, v92, v148, v80
	v_fma_f32 v81, v93, v148, v81
	v_max_f32_e32 v80, 0, v80
	v_max_f32_e32 v81, 0, v81
	v_fma_f32 v82, v94, v148, v82
	v_fmac_f32_e32 v83, v95, v148
	v_max_f32_e32 v82, 0, v82
	v_max_f32_e32 v83, 0, v83
	v_mul_f32_e32 v80, v80, v80
	v_mul_f32_e32 v81, v81, v81
	v_cvt_pk_bf16_f32 v80, v80, v81
	v_mul_f32_e32 v81, v82, v82
	v_mul_f32_e32 v82, v83, v83
	v_cvt_pk_bf16_f32 v81, v81, v82
	ds_write_b64 v112, v[80:81] offset:176
	ds_read_b128 v[80:83], v130 offset:384
	s_waitcnt lgkmcnt(0)
	v_fma_f32 v64, v64, v148, v80
	v_fma_f32 v65, v65, v148, v81
	v_max_f32_e32 v64, 0, v64
	v_max_f32_e32 v65, 0, v65
	v_fma_f32 v66, v66, v148, v82
	v_fmac_f32_e32 v83, v67, v148
	v_max_f32_e32 v66, 0, v66
	v_max_f32_e32 v67, 0, v83
	v_mul_f32_e32 v64, v64, v64
	v_mul_f32_e32 v65, v65, v65
	v_cvt_pk_bf16_f32 v64, v64, v65
	v_mul_f32_e32 v65, v66, v66
	v_mul_f32_e32 v66, v67, v67
	v_cvt_pk_bf16_f32 v65, v65, v66
	ds_write_b64 v112, v[64:65] offset:192
	ds_read_b128 v[64:67], v130 offset:416
	s_waitcnt lgkmcnt(0)
	v_fma_f32 v64, v68, v148, v64
	v_fma_f32 v65, v69, v148, v65
	v_max_f32_e32 v64, 0, v64
	v_max_f32_e32 v65, 0, v65
	v_fma_f32 v66, v70, v148, v66
	v_fmac_f32_e32 v67, v71, v148
	v_max_f32_e32 v66, 0, v66
	v_max_f32_e32 v67, 0, v67
	v_mul_f32_e32 v64, v64, v64
	v_mul_f32_e32 v65, v65, v65
	v_cvt_pk_bf16_f32 v64, v64, v65
	v_mul_f32_e32 v65, v66, v66
	v_mul_f32_e32 v66, v67, v67
	v_cvt_pk_bf16_f32 v65, v65, v66
	ds_write_b64 v112, v[64:65] offset:208
	ds_read_b128 v[64:67], v130 offset:448
	v_or_b32_e32 v68, v145, v128
	v_mad_u32_u24 v108, v107, s4, v68
	s_waitcnt lgkmcnt(0)
	v_fma_f32 v64, v72, v148, v64
	v_fma_f32 v65, v73, v148, v65
	v_max_f32_e32 v64, 0, v64
	v_max_f32_e32 v65, 0, v65
	v_fma_f32 v66, v74, v148, v66
	v_fmac_f32_e32 v67, v75, v148
	v_max_f32_e32 v66, 0, v66
	v_max_f32_e32 v67, 0, v67
	v_mul_f32_e32 v64, v64, v64
	v_mul_f32_e32 v65, v65, v65
	v_cvt_pk_bf16_f32 v64, v64, v65
	v_mul_f32_e32 v65, v66, v66
	v_mul_f32_e32 v66, v67, v67
	v_cvt_pk_bf16_f32 v65, v65, v66
	ds_write_b64 v112, v[64:65] offset:224
	ds_read_b128 v[64:67], v130 offset:480
	s_waitcnt lgkmcnt(0)
	v_fma_f32 v64, v76, v148, v64
	v_fma_f32 v65, v77, v148, v65
	v_max_f32_e32 v64, 0, v64
	v_max_f32_e32 v65, 0, v65
	v_fma_f32 v66, v78, v148, v66
	v_fmac_f32_e32 v67, v79, v148
	v_max_f32_e32 v66, 0, v66
	v_max_f32_e32 v67, 0, v67
	v_mul_f32_e32 v64, v64, v64
	v_mul_f32_e32 v65, v65, v65
	v_cvt_pk_bf16_f32 v64, v64, v65
	v_mul_f32_e32 v65, v66, v66
	v_mul_f32_e32 v66, v67, v67
	v_cvt_pk_bf16_f32 v65, v65, v66
	ds_write_b64 v112, v[64:65] offset:240
	v_or_b32_e32 v64, v106, v107
	v_or_b32_e32 v77, 4, v107
	v_ashrrev_i32_e32 v65, 31, v64
	v_mad_u32_u24 v76, v77, s4, v68
	v_lshlrev_b64 v[104:105], 13, v[64:65]
	ds_read_b128 v[78:81], v76 offset:1088
	ds_read_b128 v[82:85], v76 offset:2176
	ds_read_b128 v[86:89], v108
	ds_read_b32 v109, v146 offset:128
	ds_read_b128 v[90:93], v76
	ds_read_b128 v[94:97], v130
	ds_read_b128 v[98:101], v76 offset:3264
	ds_read_b128 v[72:75], v76 offset:4352
	ds_read_b128 v[68:71], v76 offset:5440
	ds_read_b128 v[64:67], v76 offset:6528
	s_waitcnt lgkmcnt(4)
	v_fma_f32 v48, v48, v109, v94
	v_fma_f32 v49, v49, v109, v95
	v_max_f32_e32 v48, 0, v48
	v_max_f32_e32 v49, 0, v49
	v_fma_f32 v50, v50, v109, v96
	v_fmac_f32_e32 v97, v51, v109
	v_max_f32_e32 v50, 0, v50
	v_max_f32_e32 v51, 0, v97
	v_mul_f32_e32 v48, v48, v48
	v_mul_f32_e32 v49, v49, v49
	v_cvt_pk_bf16_f32 v48, v48, v49
	v_mul_f32_e32 v49, v50, v50
	v_mul_f32_e32 v50, v51, v51
	v_cvt_pk_bf16_f32 v49, v49, v50
	ds_write_b64 v112, v[48:49]
	ds_read_b128 v[94:97], v130 offset:32
	v_lshl_add_u64 v[50:51], s[42:43], 0, v[104:105]
	v_lshlrev_b64 v[48:49], 1, v[102:103]
	v_lshl_add_u64 v[50:51], v[50:51], 0, v[48:49]
	v_lshl_add_u64 v[102:103], v[50:51], 0, v[128:129]
	s_waitcnt lgkmcnt(0)
	v_fma_f32 v50, v52, v109, v94
	v_fma_f32 v51, v53, v109, v95
	v_max_f32_e32 v50, 0, v50
	v_max_f32_e32 v51, 0, v51
	v_fma_f32 v52, v54, v109, v96
	v_fmac_f32_e32 v97, v55, v109
	v_max_f32_e32 v52, 0, v52
	v_max_f32_e32 v53, 0, v97
	v_mul_f32_e32 v50, v50, v50
	v_mul_f32_e32 v51, v51, v51
	v_cvt_pk_bf16_f32 v50, v50, v51
	v_mul_f32_e32 v51, v52, v52
	v_mul_f32_e32 v52, v53, v53
	v_cvt_pk_bf16_f32 v51, v51, v52
	ds_write_b64 v112, v[50:51] offset:16
	ds_read_b128 v[50:53], v130 offset:64
	v_or_b32_e32 v54, v106, v77
	v_ashrrev_i32_e32 v55, 31, v54
	v_lshlrev_b64 v[54:55], 13, v[54:55]
	v_lshl_add_u64 v[54:55], s[42:43], 0, v[54:55]
	s_waitcnt lgkmcnt(0)
	v_fma_f32 v50, v56, v109, v50
	v_fma_f32 v51, v57, v109, v51
	v_max_f32_e32 v50, 0, v50
	v_max_f32_e32 v51, 0, v51
	v_fma_f32 v52, v58, v109, v52
	v_fmac_f32_e32 v53, v59, v109
	v_max_f32_e32 v52, 0, v52
	v_max_f32_e32 v53, 0, v53
	v_mul_f32_e32 v50, v50, v50
	v_mul_f32_e32 v51, v51, v51
	v_cvt_pk_bf16_f32 v50, v50, v51
	v_mul_f32_e32 v51, v52, v52
	v_mul_f32_e32 v52, v53, v53
	v_cvt_pk_bf16_f32 v51, v51, v52
	ds_write_b64 v112, v[50:51] offset:32
	ds_read_b128 v[50:53], v130 offset:96
	v_or_b32_e32 v56, 8, v107
	v_lshl_add_u64 v[54:55], v[54:55], 0, v[48:49]
	v_lshl_add_u64 v[54:55], v[54:55], 0, v[128:129]
	global_store_dwordx4 v[54:55], v[90:93], off nt
	s_waitcnt lgkmcnt(0)
	v_fma_f32 v50, v60, v109, v50
	v_fma_f32 v51, v61, v109, v51
	v_max_f32_e32 v50, 0, v50
	v_max_f32_e32 v51, 0, v51
	v_fma_f32 v52, v62, v109, v52
	v_fmac_f32_e32 v53, v63, v109
	v_max_f32_e32 v52, 0, v52
	v_max_f32_e32 v53, 0, v53
	v_mul_f32_e32 v50, v50, v50
	v_mul_f32_e32 v51, v51, v51
	v_cvt_pk_bf16_f32 v50, v50, v51
	v_mul_f32_e32 v51, v52, v52
	v_mul_f32_e32 v52, v53, v53
	v_cvt_pk_bf16_f32 v51, v51, v52
	ds_write_b64 v112, v[50:51] offset:48
	ds_read_b128 v[50:53], v130 offset:128
	v_or_b32_e32 v54, v106, v56
	v_ashrrev_i32_e32 v55, 31, v54
	v_lshlrev_b64 v[54:55], 13, v[54:55]
	global_store_dwordx4 v[102:103], v[86:89], off nt
	s_waitcnt lgkmcnt(0)
	v_fma_f32 v32, v32, v109, v50
	v_fma_f32 v33, v33, v109, v51
	v_max_f32_e32 v32, 0, v32
	v_max_f32_e32 v33, 0, v33
	v_fma_f32 v34, v34, v109, v52
	v_fmac_f32_e32 v53, v35, v109
	v_max_f32_e32 v34, 0, v34
	v_max_f32_e32 v35, 0, v53
	v_mul_f32_e32 v32, v32, v32
	v_mul_f32_e32 v33, v33, v33
	v_cvt_pk_bf16_f32 v32, v32, v33
	v_mul_f32_e32 v33, v34, v34
	v_mul_f32_e32 v34, v35, v35
	v_cvt_pk_bf16_f32 v33, v33, v34
	ds_write_b64 v112, v[32:33] offset:64
	ds_read_b128 v[32:35], v130 offset:160
	v_lshl_add_u64 v[50:51], s[42:43], 0, v[54:55]
	v_lshl_add_u64 v[50:51], v[50:51], 0, v[48:49]
	v_lshl_add_u64 v[50:51], v[50:51], 0, v[128:129]
	global_store_dwordx4 v[50:51], v[78:81], off nt
	s_waitcnt lgkmcnt(0)
	v_fma_f32 v32, v36, v109, v32
	v_fma_f32 v33, v37, v109, v33
	v_max_f32_e32 v32, 0, v32
	v_max_f32_e32 v33, 0, v33
	v_fma_f32 v34, v38, v109, v34
	v_fmac_f32_e32 v35, v39, v109
	v_max_f32_e32 v34, 0, v34
	v_max_f32_e32 v35, 0, v35
	v_mul_f32_e32 v32, v32, v32
	v_mul_f32_e32 v33, v33, v33
	v_cvt_pk_bf16_f32 v32, v32, v33
	v_mul_f32_e32 v33, v34, v34
	v_mul_f32_e32 v34, v35, v35
	v_cvt_pk_bf16_f32 v33, v33, v34
	ds_write_b64 v112, v[32:33] offset:80
	ds_read_b128 v[32:35], v130 offset:192
	v_or_b32_e32 v38, 12, v107
	v_or_b32_e32 v39, 16, v107
	v_or_b32_e32 v36, v106, v38
	v_ashrrev_i32_e32 v37, 31, v36
	s_waitcnt lgkmcnt(0)
	v_fma_f32 v32, v40, v109, v32
	v_fma_f32 v33, v41, v109, v33
	v_max_f32_e32 v32, 0, v32
	v_max_f32_e32 v33, 0, v33
	v_fma_f32 v34, v42, v109, v34
	v_fmac_f32_e32 v35, v43, v109
	v_max_f32_e32 v34, 0, v34
	v_max_f32_e32 v35, 0, v35
	v_mul_f32_e32 v32, v32, v32
	v_mul_f32_e32 v33, v33, v33
	v_cvt_pk_bf16_f32 v32, v32, v33
	v_mul_f32_e32 v33, v34, v34
	v_mul_f32_e32 v34, v35, v35
	v_cvt_pk_bf16_f32 v33, v33, v34
	ds_write_b64 v112, v[32:33] offset:96
	ds_read_b128 v[32:35], v130 offset:224
	v_lshlrev_b64 v[36:37], 13, v[36:37]
	v_lshl_add_u64 v[36:37], s[42:43], 0, v[36:37]
	v_lshl_add_u64 v[36:37], v[36:37], 0, v[48:49]
	v_lshl_add_u64 v[36:37], v[36:37], 0, v[128:129]
	s_waitcnt lgkmcnt(0)
	v_fma_f32 v32, v44, v109, v32
	v_fma_f32 v33, v45, v109, v33
	v_max_f32_e32 v32, 0, v32
	v_max_f32_e32 v33, 0, v33
	v_fma_f32 v34, v46, v109, v34
	v_fmac_f32_e32 v35, v47, v109
	v_max_f32_e32 v34, 0, v34
	v_max_f32_e32 v35, 0, v35
	v_mul_f32_e32 v32, v32, v32
	v_mul_f32_e32 v33, v33, v33
	v_cvt_pk_bf16_f32 v32, v32, v33
	v_mul_f32_e32 v33, v34, v34
	v_mul_f32_e32 v34, v35, v35
	v_cvt_pk_bf16_f32 v33, v33, v34
	ds_write_b64 v112, v[32:33] offset:112
	ds_read_b128 v[32:35], v130 offset:256
	global_store_dwordx4 v[36:37], v[82:85], off nt
	v_or_b32_e32 v36, v106, v39
	v_ashrrev_i32_e32 v37, 31, v36
	v_lshlrev_b64 v[36:37], 13, v[36:37]
	s_waitcnt lgkmcnt(0)
	v_fma_f32 v16, v16, v109, v32
	v_fma_f32 v17, v17, v109, v33
	v_max_f32_e32 v16, 0, v16
	v_max_f32_e32 v17, 0, v17
	v_fma_f32 v18, v18, v109, v34
	v_fmac_f32_e32 v35, v19, v109
	v_max_f32_e32 v18, 0, v18
	v_max_f32_e32 v19, 0, v35
	v_mul_f32_e32 v16, v16, v16
	v_mul_f32_e32 v17, v17, v17
	v_cvt_pk_bf16_f32 v16, v16, v17
	v_mul_f32_e32 v17, v18, v18
	v_mul_f32_e32 v18, v19, v19
	v_cvt_pk_bf16_f32 v17, v17, v18
	ds_write_b64 v112, v[16:17] offset:128
	ds_read_b128 v[16:19], v130 offset:288
	v_lshl_add_u64 v[32:33], s[42:43], 0, v[36:37]
	v_lshl_add_u64 v[32:33], v[32:33], 0, v[48:49]
	v_lshl_add_u64 v[32:33], v[32:33], 0, v[128:129]
	global_store_dwordx4 v[32:33], v[98:101], off nt
	s_waitcnt lgkmcnt(0)
	v_fma_f32 v16, v20, v109, v16
	v_fma_f32 v17, v21, v109, v17
	v_max_f32_e32 v16, 0, v16
	v_max_f32_e32 v17, 0, v17
	v_fma_f32 v18, v22, v109, v18
	v_fmac_f32_e32 v19, v23, v109
	v_max_f32_e32 v18, 0, v18
	v_max_f32_e32 v19, 0, v19
	v_mul_f32_e32 v16, v16, v16
	v_mul_f32_e32 v17, v17, v17
	v_cvt_pk_bf16_f32 v16, v16, v17
	v_mul_f32_e32 v17, v18, v18
	v_mul_f32_e32 v18, v19, v19
	v_cvt_pk_bf16_f32 v17, v17, v18
	ds_write_b64 v112, v[16:17] offset:144
	ds_read_b128 v[16:19], v130 offset:320
	v_or_b32_e32 v22, 20, v107
	v_or_b32_e32 v20, v106, v22
	v_ashrrev_i32_e32 v21, 31, v20
	v_lshlrev_b64 v[20:21], 13, v[20:21]
	s_waitcnt lgkmcnt(0)
	v_fma_f32 v16, v24, v109, v16
	v_fma_f32 v17, v25, v109, v17
	v_max_f32_e32 v16, 0, v16
	v_max_f32_e32 v17, 0, v17
	v_fma_f32 v18, v26, v109, v18
	v_fmac_f32_e32 v19, v27, v109
	v_max_f32_e32 v18, 0, v18
	v_max_f32_e32 v19, 0, v19
	v_mul_f32_e32 v16, v16, v16
	v_mul_f32_e32 v17, v17, v17
	v_cvt_pk_bf16_f32 v16, v16, v17
	v_mul_f32_e32 v17, v18, v18
	v_mul_f32_e32 v18, v19, v19
	v_cvt_pk_bf16_f32 v17, v17, v18
	ds_write_b64 v112, v[16:17] offset:160
	ds_read_b128 v[16:19], v130 offset:352
	v_lshl_add_u64 v[20:21], s[42:43], 0, v[20:21]
	v_lshl_add_u64 v[20:21], v[20:21], 0, v[48:49]
	v_lshl_add_u64 v[20:21], v[20:21], 0, v[128:129]
	v_or_b32_e32 v23, 24, v107
	s_waitcnt lgkmcnt(0)
	v_fma_f32 v16, v28, v109, v16
	v_fma_f32 v17, v29, v109, v17
	v_max_f32_e32 v16, 0, v16
	v_max_f32_e32 v17, 0, v17
	v_fma_f32 v18, v30, v109, v18
	v_fmac_f32_e32 v19, v31, v109
	v_max_f32_e32 v18, 0, v18
	v_max_f32_e32 v19, 0, v19
	v_mul_f32_e32 v16, v16, v16
	v_mul_f32_e32 v17, v17, v17
	v_cvt_pk_bf16_f32 v16, v16, v17
	v_mul_f32_e32 v17, v18, v18
	v_mul_f32_e32 v18, v19, v19
	v_cvt_pk_bf16_f32 v17, v17, v18
	ds_write_b64 v112, v[16:17] offset:176
	ds_read_b128 v[16:19], v130 offset:384
	global_store_dwordx4 v[20:21], v[72:75], off nt
	v_or_b32_e32 v20, v106, v23
	v_ashrrev_i32_e32 v21, 31, v20
	v_lshlrev_b64 v[20:21], 13, v[20:21]
	s_waitcnt lgkmcnt(0)
	v_fma_f32 v0, v0, v109, v16
	v_fma_f32 v1, v1, v109, v17
	v_max_f32_e32 v0, 0, v0
	v_max_f32_e32 v1, 0, v1
	v_fma_f32 v2, v2, v109, v18
	v_fmac_f32_e32 v19, v3, v109
	v_max_f32_e32 v2, 0, v2
	v_max_f32_e32 v3, 0, v19
	v_mul_f32_e32 v0, v0, v0
	v_mul_f32_e32 v1, v1, v1
	v_cvt_pk_bf16_f32 v0, v0, v1
	v_mul_f32_e32 v1, v2, v2
	v_mul_f32_e32 v2, v3, v3
	v_cvt_pk_bf16_f32 v1, v1, v2
	ds_write_b64 v112, v[0:1] offset:192
	ds_read_b128 v[0:3], v130 offset:416
	v_lshl_add_u64 v[16:17], s[42:43], 0, v[20:21]
	v_lshl_add_u64 v[16:17], v[16:17], 0, v[48:49]
	v_lshl_add_u64 v[16:17], v[16:17], 0, v[128:129]
	global_store_dwordx4 v[16:17], v[68:71], off nt
	s_waitcnt lgkmcnt(0)
	v_fma_f32 v0, v4, v109, v0
	v_fma_f32 v1, v5, v109, v1
	v_max_f32_e32 v0, 0, v0
	v_max_f32_e32 v1, 0, v1
	v_fma_f32 v2, v6, v109, v2
	v_fmac_f32_e32 v3, v7, v109
	v_max_f32_e32 v2, 0, v2
	v_max_f32_e32 v3, 0, v3
	v_mul_f32_e32 v0, v0, v0
	v_mul_f32_e32 v1, v1, v1
	v_cvt_pk_bf16_f32 v0, v0, v1
	v_mul_f32_e32 v1, v2, v2
	v_mul_f32_e32 v2, v3, v3
	v_cvt_pk_bf16_f32 v1, v1, v2
	ds_write_b64 v112, v[0:1] offset:208
	ds_read_b128 v[0:3], v130 offset:448
	v_or_b32_e32 v16, 28, v107
	v_or_b32_e32 v4, v106, v16
	v_ashrrev_i32_e32 v5, 31, v4
	v_lshlrev_b64 v[4:5], 13, v[4:5]
	s_waitcnt lgkmcnt(0)
	v_fma_f32 v0, v8, v109, v0
	v_fma_f32 v1, v9, v109, v1
	v_max_f32_e32 v0, 0, v0
	v_max_f32_e32 v1, 0, v1
	v_fma_f32 v2, v10, v109, v2
	v_fmac_f32_e32 v3, v11, v109
	v_max_f32_e32 v2, 0, v2
	v_max_f32_e32 v3, 0, v3
	v_mul_f32_e32 v0, v0, v0
	v_mul_f32_e32 v1, v1, v1
	v_cvt_pk_bf16_f32 v0, v0, v1
	v_mul_f32_e32 v1, v2, v2
	v_mul_f32_e32 v2, v3, v3
	v_cvt_pk_bf16_f32 v1, v1, v2
	ds_write_b64 v112, v[0:1] offset:224
	ds_read_b128 v[0:3], v130 offset:480
	v_lshl_add_u64 v[4:5], s[42:43], 0, v[4:5]
	v_lshl_add_u64 v[4:5], v[4:5], 0, v[48:49]
	v_lshl_add_u64 v[4:5], v[4:5], 0, v[128:129]
	v_or_b32_e32 v10, 32, v106
	s_waitcnt lgkmcnt(0)
	v_fma_f32 v0, v12, v109, v0
	v_fma_f32 v1, v13, v109, v1
	v_max_f32_e32 v0, 0, v0
	v_max_f32_e32 v1, 0, v1
	v_fma_f32 v2, v14, v109, v2
	v_fmac_f32_e32 v3, v15, v109
	v_max_f32_e32 v2, 0, v2
	v_max_f32_e32 v3, 0, v3
	v_mul_f32_e32 v0, v0, v0
	v_mul_f32_e32 v1, v1, v1
	v_cvt_pk_bf16_f32 v0, v0, v1
	v_mul_f32_e32 v1, v2, v2
	v_mul_f32_e32 v2, v3, v3
	v_cvt_pk_bf16_f32 v1, v1, v2
	global_store_dwordx4 v[4:5], v[64:67], off nt
	ds_write_b64 v112, v[0:1] offset:240
	v_or_b32_e32 v4, v10, v107
	ds_read_b128 v[0:3], v108
	v_ashrrev_i32_e32 v5, 31, v4
	v_lshlrev_b64 v[4:5], 13, v[4:5]
	v_lshl_add_u64 v[4:5], s[42:43], 0, v[4:5]
	v_lshl_add_u64 v[4:5], v[4:5], 0, v[48:49]
	v_lshl_add_u64 v[8:9], v[4:5], 0, v[128:129]
	ds_read_b128 v[4:7], v76
	s_waitcnt lgkmcnt(1)
	global_store_dwordx4 v[8:9], v[0:3], off nt
	s_nop 1
	v_or_b32_e32 v0, v10, v77
	v_ashrrev_i32_e32 v1, 31, v0
	v_lshlrev_b64 v[0:1], 13, v[0:1]
	v_lshl_add_u64 v[0:1], s[42:43], 0, v[0:1]
	v_lshl_add_u64 v[0:1], v[0:1], 0, v[48:49]
	v_lshl_add_u64 v[0:1], v[0:1], 0, v[128:129]
	s_waitcnt lgkmcnt(0)
	global_store_dwordx4 v[0:1], v[4:7], off nt
	ds_read_b128 v[0:3], v76 offset:1088
	s_nop 0
	v_or_b32_e32 v4, v10, v56
	v_ashrrev_i32_e32 v5, 31, v4
	v_lshlrev_b64 v[4:5], 13, v[4:5]
	v_lshl_add_u64 v[4:5], s[42:43], 0, v[4:5]
	v_lshl_add_u64 v[4:5], v[4:5], 0, v[48:49]
	v_lshl_add_u64 v[8:9], v[4:5], 0, v[128:129]
	ds_read_b128 v[4:7], v76 offset:2176
	s_waitcnt lgkmcnt(1)
	global_store_dwordx4 v[8:9], v[0:3], off nt
	s_nop 1
	v_or_b32_e32 v0, v10, v38
	v_ashrrev_i32_e32 v1, 31, v0
	v_lshlrev_b64 v[0:1], 13, v[0:1]
	v_lshl_add_u64 v[0:1], s[42:43], 0, v[0:1]
	v_lshl_add_u64 v[0:1], v[0:1], 0, v[48:49]
	v_lshl_add_u64 v[0:1], v[0:1], 0, v[128:129]
	s_waitcnt lgkmcnt(0)
	global_store_dwordx4 v[0:1], v[4:7], off nt
	ds_read_b128 v[0:3], v76 offset:3264
	s_nop 0
	v_or_b32_e32 v4, v10, v39
	v_ashrrev_i32_e32 v5, 31, v4
	v_lshlrev_b64 v[4:5], 13, v[4:5]
	v_lshl_add_u64 v[4:5], s[42:43], 0, v[4:5]
	v_lshl_add_u64 v[4:5], v[4:5], 0, v[48:49]
	v_lshl_add_u64 v[8:9], v[4:5], 0, v[128:129]
	ds_read_b128 v[4:7], v76 offset:4352
	s_waitcnt lgkmcnt(1)
	global_store_dwordx4 v[8:9], v[0:3], off nt
	s_nop 1
	v_or_b32_e32 v0, v10, v22
	v_ashrrev_i32_e32 v1, 31, v0
	v_lshlrev_b64 v[0:1], 13, v[0:1]
	v_lshl_add_u64 v[0:1], s[42:43], 0, v[0:1]
	v_lshl_add_u64 v[0:1], v[0:1], 0, v[48:49]
	v_lshl_add_u64 v[0:1], v[0:1], 0, v[128:129]
	s_waitcnt lgkmcnt(0)
	global_store_dwordx4 v[0:1], v[4:7], off nt
	ds_read_b128 v[0:3], v76 offset:5440
	s_nop 0
	v_or_b32_e32 v4, v10, v23
	v_ashrrev_i32_e32 v5, 31, v4
	v_lshlrev_b64 v[4:5], 13, v[4:5]
	v_lshl_add_u64 v[4:5], s[42:43], 0, v[4:5]
	v_lshl_add_u64 v[4:5], v[4:5], 0, v[48:49]
	v_lshl_add_u64 v[8:9], v[4:5], 0, v[128:129]
	ds_read_b128 v[4:7], v76 offset:6528
	s_waitcnt lgkmcnt(1)
	global_store_dwordx4 v[8:9], v[0:3], off nt
	s_nop 1
	v_or_b32_e32 v0, v10, v16
	v_ashrrev_i32_e32 v1, 31, v0
	v_lshlrev_b64 v[0:1], 13, v[0:1]
	v_lshl_add_u64 v[0:1], s[42:43], 0, v[0:1]
	v_lshl_add_u64 v[0:1], v[0:1], 0, v[48:49]
	v_lshl_add_u64 v[0:1], v[0:1], 0, v[128:129]
	s_waitcnt lgkmcnt(0)
	global_store_dwordx4 v[0:1], v[4:7], off nt
	s_cbranch_scc0 .LBB0_1370
